# layer-0 w_out GEMM: the 32 context-row tiles split 4-way along K (8 k-tiles each on 128 workgroups, finisher adds three partial sets), the other 128 workgroups do the layer-1 w_in transposes
# baseline (speedup 1.0000x reference)
.LBB0_1159:
	s_or_b64 exec, exec, s[2:3]
	v_readlane_b32 s0, v254, 56
	v_readlane_b32 s1, v254, 57
	s_xor_b64 s[2:3], s[0:1], -1
	v_readlane_b32 s0, v254, 36
	v_readlane_b32 s1, v254, 37
	s_andn2_b64 vcc, exec, s[0:1]
	s_waitcnt lgkmcnt(0)
	s_barrier
	s_cbranch_vccnz .LBB0_1277
	v_readlane_b32 s0, v254, 56
	v_readlane_b32 s1, v254, 57
	s_and_b64 s[0:1], s[0:1], exec
	s_cselect_b32 s16, 0x44, 64
	s_lshl_b32 s46, s16, 3
	v_readlane_b32 s1, v254, 39
	v_readlane_b32 s9, v254, 0
	s_mul_hi_u32 s1, s46, s1
	v_readlane_b32 s10, v254, 38
	s_cmp_lt_i32 s9, s46
	s_mul_i32 s1, s1, s10
	s_cselect_b64 s[12:13], -1, 0
	v_readlane_b32 s20, v255, 0
	s_sub_i32 s1, s46, s1
	s_lshl_b32 s0, s20, 22
	s_sub_i32 s8, s1, s10
	s_cmp_ge_u32 s1, s10
	s_cselect_b32 s1, s8, s1
	s_sub_i32 s8, s1, s10
	s_cmp_ge_u32 s1, s10
	s_cselect_b32 s1, s8, s1
	v_readlane_b32 s8, v254, 1
	s_cmpk_eq_u32 s8, 0x100
	s_cselect_b32 s8, 96, 0
	s_cmpk_eq_u32 s16, 0x44
	s_cselect_b32 s8, s8, 0
	s_add_u32 s1, s1, s8
	s_add_u32 s46, s46, s8
	v_readlane_b32 s10, v254, 1
	s_sub_i32 s47, s10, s1
	v_readlane_b32 s21, v255, 1
	s_cmp_ge_i32 s9, s1
	s_mov_b32 s8, s20
	s_cselect_b64 s[14:15], -1, 0
	s_sub_i32 s52, s9, s1
	s_mov_b32 s21, s17
	v_writelane_b32 v255, s8, 0
	s_lshl_b32 s53, s47, 1
	s_lshl_b64 s[20:21], s[20:21], 23
	v_writelane_b32 v255, s9, 1
	s_mov_b32 s54, 0
	s_lshl_b32 s55, s0, 1
	v_readlane_b32 s11, v254, 2
	s_branch .LBB0_1163

.LBB0_1165:
	s_or_b64 exec, exec, s[0:1]
	s_cmp_eq_u32 s3, 3
	s_cbranch_scc1 .Lgo_fz_epi
	s_cmp_eq_u32 s3, 0
	s_cbranch_scc1 .Lgo_sk_epi
	s_mul_i32 s2, s32, 3
	s_cmp_eq_u32 s3, 2
	s_cbranch_scc0 .Lgo_sk_sl
	s_lshr_b32 s94, s94, 10
	s_add_u32 s2, s2, s94
	s_sub_u32 s2, s2, 1
.Lgo_sk_sl:
	s_lshl_b32 s2, s2, 18
	s_load_dwordx2 s[94:95], s[88:89], 0x168
	s_load_dwordx2 s[98:99], s[88:89], 0x170
	v_lshrrev_b32_e32 v170, 6, v167
	v_and_b32_e32 v171, 63, v167
	v_lshlrev_b32_e32 v170, 15, v170
	v_lshl_add_u32 v170, v171, 4, v170
	s_lshl_b32 s32, s32, 2
	s_add_u32 s32, s32, 0x180
	v_mov_b32_e32 v171, s32
	v_readfirstlane_b32 s32, v167
	s_waitcnt lgkmcnt(0)
	s_add_u32 s94, s94, s2
	s_addc_u32 s95, s95, 0
	s_cmp_eq_u32 s3, 2
	s_cbranch_scc0 .Lgo_sk_fin
	s_nop 7
	s_nop 7
	global_store_dwordx4 v170, v[0:3], s[94:95] sc0 sc1
	global_store_dwordx4 v170, v[4:7], s[94:95] offset:1024 sc0 sc1
	global_store_dwordx4 v170, v[8:11], s[94:95] offset:2048 sc0 sc1
	global_store_dwordx4 v170, v[12:15], s[94:95] offset:3072 sc0 sc1
	v_add_u32_e32 v170, 0x1000, v170
	global_store_dwordx4 v170, v[16:19], s[94:95] sc0 sc1
	global_store_dwordx4 v170, v[20:23], s[94:95] offset:1024 sc0 sc1
	global_store_dwordx4 v170, v[24:27], s[94:95] offset:2048 sc0 sc1
	global_store_dwordx4 v170, v[28:31], s[94:95] offset:3072 sc0 sc1
	v_add_u32_e32 v170, 0x1000, v170
	global_store_dwordx4 v170, v[32:35], s[94:95] sc0 sc1
	global_store_dwordx4 v170, v[36:39], s[94:95] offset:1024 sc0 sc1
	global_store_dwordx4 v170, v[40:43], s[94:95] offset:2048 sc0 sc1
	global_store_dwordx4 v170, v[44:47], s[94:95] offset:3072 sc0 sc1
	v_add_u32_e32 v170, 0x1000, v170
	global_store_dwordx4 v170, v[48:51], s[94:95] sc0 sc1
	global_store_dwordx4 v170, v[52:55], s[94:95] offset:1024 sc0 sc1
	global_store_dwordx4 v170, v[56:59], s[94:95] offset:2048 sc0 sc1
	global_store_dwordx4 v170, v[60:63], s[94:95] offset:3072 sc0 sc1
	v_add_u32_e32 v170, 0x1000, v170
	global_store_dwordx4 v170, v[64:67], s[94:95] sc0 sc1
	global_store_dwordx4 v170, v[68:71], s[94:95] offset:1024 sc0 sc1
	global_store_dwordx4 v170, v[72:75], s[94:95] offset:2048 sc0 sc1
	global_store_dwordx4 v170, v[76:79], s[94:95] offset:3072 sc0 sc1
	v_add_u32_e32 v170, 0x1000, v170
	global_store_dwordx4 v170, v[80:83], s[94:95] sc0 sc1
	global_store_dwordx4 v170, v[84:87], s[94:95] offset:1024 sc0 sc1
	global_store_dwordx4 v170, v[88:91], s[94:95] offset:2048 sc0 sc1
	global_store_dwordx4 v170, v[92:95], s[94:95] offset:3072 sc0 sc1
	v_add_u32_e32 v170, 0x1000, v170
	global_store_dwordx4 v170, v[96:99], s[94:95] sc0 sc1
	global_store_dwordx4 v170, v[100:103], s[94:95] offset:1024 sc0 sc1
	global_store_dwordx4 v170, v[104:107], s[94:95] offset:2048 sc0 sc1
	global_store_dwordx4 v170, v[108:111], s[94:95] offset:3072 sc0 sc1
	v_add_u32_e32 v170, 0x1000, v170
	global_store_dwordx4 v170, v[112:115], s[94:95] sc0 sc1
	global_store_dwordx4 v170, v[116:119], s[94:95] offset:1024 sc0 sc1
	global_store_dwordx4 v170, v[120:123], s[94:95] offset:2048 sc0 sc1
	global_store_dwordx4 v170, v[124:127], s[94:95] offset:3072 sc0 sc1
	v_add_u32_e32 v170, 0x1000, v170
	s_waitcnt vmcnt(0)
	s_barrier
	s_cmp_lt_u32 s32, 64
	s_cbranch_scc0 .Lgo_sk_pend
	s_mov_b64 exec, 1
	v_mov_b32_e32 v172, 1
	global_atomic_add v171, v172, s[98:99]
	s_waitcnt vmcnt(0)
	s_mov_b64 exec, -1

.Lgo_sk_poll:
	global_load_dword v172, v171, s[98:99] sc1
	s_waitcnt vmcnt(0)
	v_readfirstlane_b32 s3, v172
	s_cmp_ge_u32 s3, 3
	s_cbranch_scc1 .Lgo_sk_got
	s_sleep 1
	s_add_u32 s2, s2, 1
	s_cmp_lt_u32 s2, 0x200000
	s_cbranch_scc1 .Lgo_sk_poll

.Lgo_sk_wd:
	s_barrier
	s_mov_b32 s3, 3
.Lgo_sk_addloop:
	global_load_dwordx4 v[194:197], v170, s[94:95] sc0 sc1
	global_load_dwordx4 v[198:201], v170, s[94:95] offset:1024 sc0 sc1
	global_load_dwordx4 v[202:205], v170, s[94:95] offset:2048 sc0 sc1
	global_load_dwordx4 v[206:209], v170, s[94:95] offset:3072 sc0 sc1
	v_add_u32_e32 v170, 0x1000, v170
	global_load_dwordx4 v[210:213], v170, s[94:95] sc0 sc1
	global_load_dwordx4 v[214:217], v170, s[94:95] offset:1024 sc0 sc1
	global_load_dwordx4 v[218:221], v170, s[94:95] offset:2048 sc0 sc1
	global_load_dwordx4 v[222:225], v170, s[94:95] offset:3072 sc0 sc1
	v_add_u32_e32 v170, 0x1000, v170
	global_load_dwordx4 v[226:229], v170, s[94:95] sc0 sc1
	global_load_dwordx4 v[230:233], v170, s[94:95] offset:1024 sc0 sc1
	global_load_dwordx4 v[234:237], v170, s[94:95] offset:2048 sc0 sc1
	global_load_dwordx4 v[238:241], v170, s[94:95] offset:3072 sc0 sc1
	v_add_u32_e32 v170, 0x1000, v170
	global_load_dwordx4 v[242:245], v170, s[94:95] sc0 sc1
	global_load_dwordx4 v[246:249], v170, s[94:95] offset:1024 sc0 sc1
	global_load_dwordx4 v[250:253], v170, s[94:95] offset:2048 sc0 sc1
	s_waitcnt vmcnt(7)
	v_pk_add_f32 v[0:1], v[0:1], v[194:195]
	v_pk_add_f32 v[2:3], v[2:3], v[196:197]
	v_pk_add_f32 v[4:5], v[4:5], v[198:199]
	v_pk_add_f32 v[6:7], v[6:7], v[200:201]
	v_pk_add_f32 v[8:9], v[8:9], v[202:203]
	v_pk_add_f32 v[10:11], v[10:11], v[204:205]
	v_pk_add_f32 v[12:13], v[12:13], v[206:207]
	v_pk_add_f32 v[14:15], v[14:15], v[208:209]
	v_pk_add_f32 v[16:17], v[16:17], v[210:211]
	v_pk_add_f32 v[18:19], v[18:19], v[212:213]
	v_pk_add_f32 v[20:21], v[20:21], v[214:215]
	v_pk_add_f32 v[22:23], v[22:23], v[216:217]
	v_pk_add_f32 v[24:25], v[24:25], v[218:219]
	v_pk_add_f32 v[26:27], v[26:27], v[220:221]
	v_pk_add_f32 v[28:29], v[28:29], v[222:223]
	v_pk_add_f32 v[30:31], v[30:31], v[224:225]
	global_load_dwordx4 v[194:197], v170, s[94:95] offset:3072 sc0 sc1
	v_add_u32_e32 v170, 0x1000, v170
	global_load_dwordx4 v[198:201], v170, s[94:95] sc0 sc1
	global_load_dwordx4 v[202:205], v170, s[94:95] offset:1024 sc0 sc1
	global_load_dwordx4 v[206:209], v170, s[94:95] offset:2048 sc0 sc1
	global_load_dwordx4 v[210:213], v170, s[94:95] offset:3072 sc0 sc1
	v_add_u32_e32 v170, 0x1000, v170
	global_load_dwordx4 v[214:217], v170, s[94:95] sc0 sc1
	global_load_dwordx4 v[218:221], v170, s[94:95] offset:1024 sc0 sc1
	global_load_dwordx4 v[222:225], v170, s[94:95] offset:2048 sc0 sc1
	s_waitcnt vmcnt(8)
	v_pk_add_f32 v[32:33], v[32:33], v[226:227]
	v_pk_add_f32 v[34:35], v[34:35], v[228:229]
	v_pk_add_f32 v[36:37], v[36:37], v[230:231]
	v_pk_add_f32 v[38:39], v[38:39], v[232:233]
	v_pk_add_f32 v[40:41], v[40:41], v[234:235]
	v_pk_add_f32 v[42:43], v[42:43], v[236:237]
	v_pk_add_f32 v[44:45], v[44:45], v[238:239]
	v_pk_add_f32 v[46:47], v[46:47], v[240:241]
	v_pk_add_f32 v[48:49], v[48:49], v[242:243]
	v_pk_add_f32 v[50:51], v[50:51], v[244:245]
	v_pk_add_f32 v[52:53], v[52:53], v[246:247]
	v_pk_add_f32 v[54:55], v[54:55], v[248:249]
	v_pk_add_f32 v[56:57], v[56:57], v[250:251]
	v_pk_add_f32 v[58:59], v[58:59], v[252:253]
	global_load_dwordx4 v[226:229], v170, s[94:95] offset:3072 sc0 sc1
	v_add_u32_e32 v170, 0x1000, v170
	global_load_dwordx4 v[230:233], v170, s[94:95] sc0 sc1
	global_load_dwordx4 v[234:237], v170, s[94:95] offset:1024 sc0 sc1
	global_load_dwordx4 v[238:241], v170, s[94:95] offset:2048 sc0 sc1
	global_load_dwordx4 v[242:245], v170, s[94:95] offset:3072 sc0 sc1
	v_add_u32_e32 v170, 0x1000, v170
	global_load_dwordx4 v[246:249], v170, s[94:95] sc0 sc1
	global_load_dwordx4 v[250:253], v170, s[94:95] offset:1024 sc0 sc1
	s_waitcnt vmcnt(7)
	v_pk_add_f32 v[60:61], v[60:61], v[194:195]
	v_pk_add_f32 v[62:63], v[62:63], v[196:197]
	v_pk_add_f32 v[64:65], v[64:65], v[198:199]
	v_pk_add_f32 v[66:67], v[66:67], v[200:201]
	v_pk_add_f32 v[68:69], v[68:69], v[202:203]
	v_pk_add_f32 v[70:71], v[70:71], v[204:205]
	v_pk_add_f32 v[72:73], v[72:73], v[206:207]
	v_pk_add_f32 v[74:75], v[74:75], v[208:209]
	v_pk_add_f32 v[76:77], v[76:77], v[210:211]
	v_pk_add_f32 v[78:79], v[78:79], v[212:213]
	v_pk_add_f32 v[80:81], v[80:81], v[214:215]
	v_pk_add_f32 v[82:83], v[82:83], v[216:217]
	v_pk_add_f32 v[84:85], v[84:85], v[218:219]
	v_pk_add_f32 v[86:87], v[86:87], v[220:221]
	v_pk_add_f32 v[88:89], v[88:89], v[222:223]
	v_pk_add_f32 v[90:91], v[90:91], v[224:225]
	global_load_dwordx4 v[194:197], v170, s[94:95] offset:2048 sc0 sc1
	global_load_dwordx4 v[198:201], v170, s[94:95] offset:3072 sc0 sc1
	v_add_u32_e32 v170, 0x1000, v170
	s_waitcnt vmcnt(2)
	v_pk_add_f32 v[92:93], v[92:93], v[226:227]
	v_pk_add_f32 v[94:95], v[94:95], v[228:229]
	v_pk_add_f32 v[96:97], v[96:97], v[230:231]
	v_pk_add_f32 v[98:99], v[98:99], v[232:233]
	v_pk_add_f32 v[100:101], v[100:101], v[234:235]
	v_pk_add_f32 v[102:103], v[102:103], v[236:237]
	v_pk_add_f32 v[104:105], v[104:105], v[238:239]
	v_pk_add_f32 v[106:107], v[106:107], v[240:241]
	v_pk_add_f32 v[108:109], v[108:109], v[242:243]
	v_pk_add_f32 v[110:111], v[110:111], v[244:245]
	v_pk_add_f32 v[112:113], v[112:113], v[246:247]
	v_pk_add_f32 v[114:115], v[114:115], v[248:249]
	v_pk_add_f32 v[116:117], v[116:117], v[250:251]
	v_pk_add_f32 v[118:119], v[118:119], v[252:253]
	s_waitcnt vmcnt(0)
	v_pk_add_f32 v[120:121], v[120:121], v[194:195]
	v_pk_add_f32 v[122:123], v[122:123], v[196:197]
	v_pk_add_f32 v[124:125], v[124:125], v[198:199]
	v_pk_add_f32 v[126:127], v[126:127], v[200:201]
	s_sub_u32 s3, s3, 1
	s_cmp_eq_u32 s3, 0
	s_cbranch_scc1 .Lgo_sk_epi
	s_add_u32 s94, s94, 0x40000
	s_addc_u32 s95, s95, 0
	v_add_u32_e32 v170, 0xffff8000, v170
	s_branch .Lgo_sk_addloop

.Lgo_fz_epi:
	s_nop 7
	s_nop 7
	s_load_dwordx2 s[94:95], s[88:89], 0x168
	s_load_dwordx2 s[98:99], s[88:89], 0x170
	s_load_dwordx2 s[2:3], s[88:89], 0xc0
	v_and_b32_e32 v160, 15, v167
	v_bfe_u32 v161, v167, 4, 2
	v_bfe_u32 v162, v167, 6, 2
	v_lshrrev_b32_e32 v163, 8, v167
	v_lshlrev_b32_e32 v163, 6, v163
	v_lshl_add_u32 v163, v161, 2, v163
	v_lshl_add_u32 v164, v162, 5, v160
	v_readlane_b32 s32, v255, 0
	s_lshr_b32 s45, s36, 8
	s_lshl_b32 s48, s45, 3
	s_lshr_b32 s57, s34, 8
	s_add_u32 s48, s48, s57
	s_lshl_b32 s48, s48, 10
	s_lshr_b32 s57, s36, 12
	s_mul_i32 s0, s32, 5
	s_add_u32 s57, s57, s0
	s_mul_i32 s57, s57, 0x6000
	s_add_u32 s57, s57, 0x4000
	v_lshlrev_b32_e32 v237, 2, v164
	s_lshl_b32 vcc_lo, s34, 2
	v_add_u32_e32 v237, vcc_lo, v237
	v_add_u32_e32 v168, s36, v163
	v_lshlrev_b32_e32 v168, 13, v168
	v_add_u32_e32 v168, v168, v237
	v_add_u32_e32 v169, 0x2000, v168
	v_add_u32_e32 v170, 0x4000, v168
	v_add_u32_e32 v171, 0x6000, v168
	s_lshl_b32 s0, s45, 2
	s_add_u32 s0, s0, 0x204
	v_mov_b32_e32 v234, s0
	s_lshl_b32 s0, s45, 13
	v_lshl_add_u32 v235, v167, 2, s0
	s_lshl_b32 s45, s32, 4
	s_add_u32 s45, s45, 8
	s_load_dwordx2 s[36:37], s[88:89], 0xc8
	s_load_dwordx2 s[34:35], s[88:89], 0xf0
	s_load_dwordx2 s[0:1], s[88:89], 0x0
	v_mul_f32_e32 v194, v124, v124
	v_fmac_f32_e32 v194, v120, v120
	v_fmac_f32_e32 v194, v100, v100
	v_fmac_f32_e32 v194, v96, v96
	v_mul_f32_e32 v195, v125, v125
	v_fmac_f32_e32 v195, v121, v121
	v_fmac_f32_e32 v195, v101, v101
	v_fmac_f32_e32 v195, v97, v97
	v_mul_f32_e32 v196, v126, v126
	v_fmac_f32_e32 v196, v122, v122
	v_fmac_f32_e32 v196, v102, v102
	v_fmac_f32_e32 v196, v98, v98
	v_mul_f32_e32 v197, v127, v127
	v_fmac_f32_e32 v197, v123, v123
	v_fmac_f32_e32 v197, v103, v103
	v_fmac_f32_e32 v197, v99, v99
	v_mul_f32_e32 v198, v116, v116
	v_fmac_f32_e32 v198, v112, v112
	v_fmac_f32_e32 v198, v92, v92
	v_fmac_f32_e32 v198, v88, v88
	v_mul_f32_e32 v199, v117, v117
	v_fmac_f32_e32 v199, v113, v113
	v_fmac_f32_e32 v199, v93, v93
	v_fmac_f32_e32 v199, v89, v89
	v_mul_f32_e32 v200, v118, v118
	v_fmac_f32_e32 v200, v114, v114
	v_fmac_f32_e32 v200, v94, v94
	v_fmac_f32_e32 v200, v90, v90
	v_mul_f32_e32 v201, v119, v119
	v_fmac_f32_e32 v201, v115, v115
	v_fmac_f32_e32 v201, v95, v95
	v_fmac_f32_e32 v201, v91, v91
	v_mul_f32_e32 v202, v108, v108
	v_fmac_f32_e32 v202, v104, v104
	v_fmac_f32_e32 v202, v80, v80
	v_fmac_f32_e32 v202, v72, v72
	v_mul_f32_e32 v203, v109, v109
	v_fmac_f32_e32 v203, v105, v105
	v_fmac_f32_e32 v203, v81, v81
	v_fmac_f32_e32 v203, v73, v73
	v_mul_f32_e32 v204, v110, v110
	v_fmac_f32_e32 v204, v106, v106
	v_fmac_f32_e32 v204, v82, v82
	v_fmac_f32_e32 v204, v74, v74
	v_mul_f32_e32 v205, v111, v111
	v_fmac_f32_e32 v205, v107, v107
	v_fmac_f32_e32 v205, v83, v83
	v_fmac_f32_e32 v205, v75, v75
	v_mul_f32_e32 v206, v84, v84
	v_fmac_f32_e32 v206, v76, v76
	v_fmac_f32_e32 v206, v68, v68
	v_fmac_f32_e32 v206, v64, v64
	v_mul_f32_e32 v207, v85, v85
	v_fmac_f32_e32 v207, v77, v77
	v_fmac_f32_e32 v207, v69, v69
	v_fmac_f32_e32 v207, v65, v65
	v_mul_f32_e32 v208, v86, v86
	v_fmac_f32_e32 v208, v78, v78
	v_fmac_f32_e32 v208, v70, v70
	v_fmac_f32_e32 v208, v66, v66
	v_mul_f32_e32 v209, v87, v87
	v_fmac_f32_e32 v209, v79, v79
	v_fmac_f32_e32 v209, v71, v71
	v_fmac_f32_e32 v209, v67, v67
	v_mul_f32_e32 v210, v60, v60
	v_fmac_f32_e32 v210, v56, v56
	v_fmac_f32_e32 v210, v32, v32
	v_fmac_f32_e32 v210, v24, v24
	v_mul_f32_e32 v211, v61, v61
	v_fmac_f32_e32 v211, v57, v57
	v_fmac_f32_e32 v211, v33, v33
	v_fmac_f32_e32 v211, v25, v25
	v_mul_f32_e32 v212, v62, v62
	v_fmac_f32_e32 v212, v58, v58
	v_fmac_f32_e32 v212, v34, v34
	v_fmac_f32_e32 v212, v26, v26
	v_mul_f32_e32 v213, v63, v63
	v_fmac_f32_e32 v213, v59, v59
	v_fmac_f32_e32 v213, v35, v35
	v_fmac_f32_e32 v213, v27, v27
	v_mul_f32_e32 v214, v52, v52
	v_fmac_f32_e32 v214, v48, v48
	v_fmac_f32_e32 v214, v20, v20
	v_fmac_f32_e32 v214, v16, v16
	v_mul_f32_e32 v215, v53, v53
	v_fmac_f32_e32 v215, v49, v49
	v_fmac_f32_e32 v215, v21, v21
	v_fmac_f32_e32 v215, v17, v17
	v_mul_f32_e32 v216, v54, v54
	v_fmac_f32_e32 v216, v50, v50
	v_fmac_f32_e32 v216, v22, v22
	v_fmac_f32_e32 v216, v18, v18
	v_mul_f32_e32 v217, v55, v55
	v_fmac_f32_e32 v217, v51, v51
	v_fmac_f32_e32 v217, v23, v23
	v_fmac_f32_e32 v217, v19, v19
	v_mul_f32_e32 v218, v44, v44
	v_fmac_f32_e32 v218, v40, v40
	v_fmac_f32_e32 v218, v12, v12
	v_fmac_f32_e32 v218, v8, v8
	v_mul_f32_e32 v219, v45, v45
	v_fmac_f32_e32 v219, v41, v41
	v_fmac_f32_e32 v219, v13, v13
	v_fmac_f32_e32 v219, v9, v9
	v_mul_f32_e32 v220, v46, v46
	v_fmac_f32_e32 v220, v42, v42
	v_fmac_f32_e32 v220, v14, v14
	v_fmac_f32_e32 v220, v10, v10
	v_mul_f32_e32 v221, v47, v47
	v_fmac_f32_e32 v221, v43, v43
	v_fmac_f32_e32 v221, v15, v15
	v_fmac_f32_e32 v221, v11, v11
	v_mul_f32_e32 v222, v36, v36
	v_fmac_f32_e32 v222, v28, v28
	v_fmac_f32_e32 v222, v4, v4
	v_fmac_f32_e32 v222, v0, v0
	v_mul_f32_e32 v223, v37, v37
	v_fmac_f32_e32 v223, v29, v29
	v_fmac_f32_e32 v223, v5, v5
	v_fmac_f32_e32 v223, v1, v1
	v_mul_f32_e32 v224, v38, v38
	v_fmac_f32_e32 v224, v30, v30
	v_fmac_f32_e32 v224, v6, v6
	v_fmac_f32_e32 v224, v2, v2
	v_mul_f32_e32 v225, v39, v39
	v_fmac_f32_e32 v225, v31, v31
	v_fmac_f32_e32 v225, v7, v7
	v_fmac_f32_e32 v225, v3, v3
	s_nop 1
	v_add_f32_dpp v194, v194, v194 row_ror:8 row_mask:0xf bank_mask:0xf
	v_add_f32_dpp v195, v195, v195 row_ror:8 row_mask:0xf bank_mask:0xf
	v_add_f32_dpp v196, v196, v196 row_ror:8 row_mask:0xf bank_mask:0xf
	v_add_f32_dpp v197, v197, v197 row_ror:8 row_mask:0xf bank_mask:0xf
	v_add_f32_dpp v198, v198, v198 row_ror:8 row_mask:0xf bank_mask:0xf
	v_add_f32_dpp v199, v199, v199 row_ror:8 row_mask:0xf bank_mask:0xf
	v_add_f32_dpp v200, v200, v200 row_ror:8 row_mask:0xf bank_mask:0xf
	v_add_f32_dpp v201, v201, v201 row_ror:8 row_mask:0xf bank_mask:0xf
	v_add_f32_dpp v202, v202, v202 row_ror:8 row_mask:0xf bank_mask:0xf
	v_add_f32_dpp v203, v203, v203 row_ror:8 row_mask:0xf bank_mask:0xf
	v_add_f32_dpp v204, v204, v204 row_ror:8 row_mask:0xf bank_mask:0xf
	v_add_f32_dpp v205, v205, v205 row_ror:8 row_mask:0xf bank_mask:0xf
	v_add_f32_dpp v206, v206, v206 row_ror:8 row_mask:0xf bank_mask:0xf
	v_add_f32_dpp v207, v207, v207 row_ror:8 row_mask:0xf bank_mask:0xf
	v_add_f32_dpp v208, v208, v208 row_ror:8 row_mask:0xf bank_mask:0xf
	v_add_f32_dpp v209, v209, v209 row_ror:8 row_mask:0xf bank_mask:0xf
	v_add_f32_dpp v210, v210, v210 row_ror:8 row_mask:0xf bank_mask:0xf
	v_add_f32_dpp v211, v211, v211 row_ror:8 row_mask:0xf bank_mask:0xf
	v_add_f32_dpp v212, v212, v212 row_ror:8 row_mask:0xf bank_mask:0xf
	v_add_f32_dpp v213, v213, v213 row_ror:8 row_mask:0xf bank_mask:0xf
	v_add_f32_dpp v214, v214, v214 row_ror:8 row_mask:0xf bank_mask:0xf
	v_add_f32_dpp v215, v215, v215 row_ror:8 row_mask:0xf bank_mask:0xf
	v_add_f32_dpp v216, v216, v216 row_ror:8 row_mask:0xf bank_mask:0xf
	v_add_f32_dpp v217, v217, v217 row_ror:8 row_mask:0xf bank_mask:0xf
	v_add_f32_dpp v218, v218, v218 row_ror:8 row_mask:0xf bank_mask:0xf
	v_add_f32_dpp v219, v219, v219 row_ror:8 row_mask:0xf bank_mask:0xf
	v_add_f32_dpp v220, v220, v220 row_ror:8 row_mask:0xf bank_mask:0xf
	v_add_f32_dpp v221, v221, v221 row_ror:8 row_mask:0xf bank_mask:0xf
	v_add_f32_dpp v222, v222, v222 row_ror:8 row_mask:0xf bank_mask:0xf
	v_add_f32_dpp v223, v223, v223 row_ror:8 row_mask:0xf bank_mask:0xf
	v_add_f32_dpp v224, v224, v224 row_ror:8 row_mask:0xf bank_mask:0xf
	v_add_f32_dpp v225, v225, v225 row_ror:8 row_mask:0xf bank_mask:0xf
	s_nop 1
	v_add_f32_dpp v194, v194, v194 row_ror:4 row_mask:0xf bank_mask:0xf
	v_add_f32_dpp v195, v195, v195 row_ror:4 row_mask:0xf bank_mask:0xf
	v_add_f32_dpp v196, v196, v196 row_ror:4 row_mask:0xf bank_mask:0xf
	v_add_f32_dpp v197, v197, v197 row_ror:4 row_mask:0xf bank_mask:0xf
	v_add_f32_dpp v198, v198, v198 row_ror:4 row_mask:0xf bank_mask:0xf
	v_add_f32_dpp v199, v199, v199 row_ror:4 row_mask:0xf bank_mask:0xf
	v_add_f32_dpp v200, v200, v200 row_ror:4 row_mask:0xf bank_mask:0xf
	v_add_f32_dpp v201, v201, v201 row_ror:4 row_mask:0xf bank_mask:0xf
	v_add_f32_dpp v202, v202, v202 row_ror:4 row_mask:0xf bank_mask:0xf
	v_add_f32_dpp v203, v203, v203 row_ror:4 row_mask:0xf bank_mask:0xf
	v_add_f32_dpp v204, v204, v204 row_ror:4 row_mask:0xf bank_mask:0xf
	v_add_f32_dpp v205, v205, v205 row_ror:4 row_mask:0xf bank_mask:0xf
	v_add_f32_dpp v206, v206, v206 row_ror:4 row_mask:0xf bank_mask:0xf
	v_add_f32_dpp v207, v207, v207 row_ror:4 row_mask:0xf bank_mask:0xf
	v_add_f32_dpp v208, v208, v208 row_ror:4 row_mask:0xf bank_mask:0xf
	v_add_f32_dpp v209, v209, v209 row_ror:4 row_mask:0xf bank_mask:0xf
	v_add_f32_dpp v210, v210, v210 row_ror:4 row_mask:0xf bank_mask:0xf
	v_add_f32_dpp v211, v211, v211 row_ror:4 row_mask:0xf bank_mask:0xf
	v_add_f32_dpp v212, v212, v212 row_ror:4 row_mask:0xf bank_mask:0xf
	v_add_f32_dpp v213, v213, v213 row_ror:4 row_mask:0xf bank_mask:0xf
	v_add_f32_dpp v214, v214, v214 row_ror:4 row_mask:0xf bank_mask:0xf
	v_add_f32_dpp v215, v215, v215 row_ror:4 row_mask:0xf bank_mask:0xf
	v_add_f32_dpp v216, v216, v216 row_ror:4 row_mask:0xf bank_mask:0xf
	v_add_f32_dpp v217, v217, v217 row_ror:4 row_mask:0xf bank_mask:0xf
	v_add_f32_dpp v218, v218, v218 row_ror:4 row_mask:0xf bank_mask:0xf
	v_add_f32_dpp v219, v219, v219 row_ror:4 row_mask:0xf bank_mask:0xf
	v_add_f32_dpp v220, v220, v220 row_ror:4 row_mask:0xf bank_mask:0xf
	v_add_f32_dpp v221, v221, v221 row_ror:4 row_mask:0xf bank_mask:0xf
	v_add_f32_dpp v222, v222, v222 row_ror:4 row_mask:0xf bank_mask:0xf
	v_add_f32_dpp v223, v223, v223 row_ror:4 row_mask:0xf bank_mask:0xf
	v_add_f32_dpp v224, v224, v224 row_ror:4 row_mask:0xf bank_mask:0xf
	v_add_f32_dpp v225, v225, v225 row_ror:4 row_mask:0xf bank_mask:0xf
	s_nop 1
	v_add_f32_dpp v194, v194, v194 row_ror:2 row_mask:0xf bank_mask:0xf
	v_add_f32_dpp v195, v195, v195 row_ror:2 row_mask:0xf bank_mask:0xf
	v_add_f32_dpp v196, v196, v196 row_ror:2 row_mask:0xf bank_mask:0xf
	v_add_f32_dpp v197, v197, v197 row_ror:2 row_mask:0xf bank_mask:0xf
	v_add_f32_dpp v198, v198, v198 row_ror:2 row_mask:0xf bank_mask:0xf
	v_add_f32_dpp v199, v199, v199 row_ror:2 row_mask:0xf bank_mask:0xf
	v_add_f32_dpp v200, v200, v200 row_ror:2 row_mask:0xf bank_mask:0xf
	v_add_f32_dpp v201, v201, v201 row_ror:2 row_mask:0xf bank_mask:0xf
	v_add_f32_dpp v202, v202, v202 row_ror:2 row_mask:0xf bank_mask:0xf
	v_add_f32_dpp v203, v203, v203 row_ror:2 row_mask:0xf bank_mask:0xf
	v_add_f32_dpp v204, v204, v204 row_ror:2 row_mask:0xf bank_mask:0xf
	v_add_f32_dpp v205, v205, v205 row_ror:2 row_mask:0xf bank_mask:0xf
	v_add_f32_dpp v206, v206, v206 row_ror:2 row_mask:0xf bank_mask:0xf
	v_add_f32_dpp v207, v207, v207 row_ror:2 row_mask:0xf bank_mask:0xf
	v_add_f32_dpp v208, v208, v208 row_ror:2 row_mask:0xf bank_mask:0xf
	v_add_f32_dpp v209, v209, v209 row_ror:2 row_mask:0xf bank_mask:0xf
	v_add_f32_dpp v210, v210, v210 row_ror:2 row_mask:0xf bank_mask:0xf
	v_add_f32_dpp v211, v211, v211 row_ror:2 row_mask:0xf bank_mask:0xf
	v_add_f32_dpp v212, v212, v212 row_ror:2 row_mask:0xf bank_mask:0xf
	v_add_f32_dpp v213, v213, v213 row_ror:2 row_mask:0xf bank_mask:0xf
	v_add_f32_dpp v214, v214, v214 row_ror:2 row_mask:0xf bank_mask:0xf
	v_add_f32_dpp v215, v215, v215 row_ror:2 row_mask:0xf bank_mask:0xf
	v_add_f32_dpp v216, v216, v216 row_ror:2 row_mask:0xf bank_mask:0xf
	v_add_f32_dpp v217, v217, v217 row_ror:2 row_mask:0xf bank_mask:0xf
	v_add_f32_dpp v218, v218, v218 row_ror:2 row_mask:0xf bank_mask:0xf
	v_add_f32_dpp v219, v219, v219 row_ror:2 row_mask:0xf bank_mask:0xf
	v_add_f32_dpp v220, v220, v220 row_ror:2 row_mask:0xf bank_mask:0xf
	v_add_f32_dpp v221, v221, v221 row_ror:2 row_mask:0xf bank_mask:0xf
	v_add_f32_dpp v222, v222, v222 row_ror:2 row_mask:0xf bank_mask:0xf
	v_add_f32_dpp v223, v223, v223 row_ror:2 row_mask:0xf bank_mask:0xf
	v_add_f32_dpp v224, v224, v224 row_ror:2 row_mask:0xf bank_mask:0xf
	v_add_f32_dpp v225, v225, v225 row_ror:2 row_mask:0xf bank_mask:0xf
	s_nop 1
	v_add_f32_dpp v194, v194, v194 row_ror:1 row_mask:0xf bank_mask:0xf
	v_add_f32_dpp v195, v195, v195 row_ror:1 row_mask:0xf bank_mask:0xf
	v_add_f32_dpp v196, v196, v196 row_ror:1 row_mask:0xf bank_mask:0xf
	v_add_f32_dpp v197, v197, v197 row_ror:1 row_mask:0xf bank_mask:0xf
	v_add_f32_dpp v198, v198, v198 row_ror:1 row_mask:0xf bank_mask:0xf
	v_add_f32_dpp v199, v199, v199 row_ror:1 row_mask:0xf bank_mask:0xf
	v_add_f32_dpp v200, v200, v200 row_ror:1 row_mask:0xf bank_mask:0xf
	v_add_f32_dpp v201, v201, v201 row_ror:1 row_mask:0xf bank_mask:0xf
	v_add_f32_dpp v202, v202, v202 row_ror:1 row_mask:0xf bank_mask:0xf
	v_add_f32_dpp v203, v203, v203 row_ror:1 row_mask:0xf bank_mask:0xf
	v_add_f32_dpp v204, v204, v204 row_ror:1 row_mask:0xf bank_mask:0xf
	v_add_f32_dpp v205, v205, v205 row_ror:1 row_mask:0xf bank_mask:0xf
	v_add_f32_dpp v206, v206, v206 row_ror:1 row_mask:0xf bank_mask:0xf
	v_add_f32_dpp v207, v207, v207 row_ror:1 row_mask:0xf bank_mask:0xf
	v_add_f32_dpp v208, v208, v208 row_ror:1 row_mask:0xf bank_mask:0xf
	v_add_f32_dpp v209, v209, v209 row_ror:1 row_mask:0xf bank_mask:0xf
	v_add_f32_dpp v210, v210, v210 row_ror:1 row_mask:0xf bank_mask:0xf
	v_add_f32_dpp v211, v211, v211 row_ror:1 row_mask:0xf bank_mask:0xf
	v_add_f32_dpp v212, v212, v212 row_ror:1 row_mask:0xf bank_mask:0xf
	v_add_f32_dpp v213, v213, v213 row_ror:1 row_mask:0xf bank_mask:0xf
	v_add_f32_dpp v214, v214, v214 row_ror:1 row_mask:0xf bank_mask:0xf
	v_add_f32_dpp v215, v215, v215 row_ror:1 row_mask:0xf bank_mask:0xf
	v_add_f32_dpp v216, v216, v216 row_ror:1 row_mask:0xf bank_mask:0xf
	v_add_f32_dpp v217, v217, v217 row_ror:1 row_mask:0xf bank_mask:0xf
	v_add_f32_dpp v218, v218, v218 row_ror:1 row_mask:0xf bank_mask:0xf
	v_add_f32_dpp v219, v219, v219 row_ror:1 row_mask:0xf bank_mask:0xf
	v_add_f32_dpp v220, v220, v220 row_ror:1 row_mask:0xf bank_mask:0xf
	v_add_f32_dpp v221, v221, v221 row_ror:1 row_mask:0xf bank_mask:0xf
	v_add_f32_dpp v222, v222, v222 row_ror:1 row_mask:0xf bank_mask:0xf
	v_add_f32_dpp v223, v223, v223 row_ror:1 row_mask:0xf bank_mask:0xf
	v_add_f32_dpp v224, v224, v224 row_ror:1 row_mask:0xf bank_mask:0xf
	v_add_f32_dpp v225, v225, v225 row_ror:1 row_mask:0xf bank_mask:0xf
	v_lshlrev_b32_e32 v236, 10, v162
	v_lshl_add_u32 v236, v163, 2, v236
	v_add_u32_e32 v236, 0x20000, v236
	v_cmp_eq_u32_e32 vcc, 0, v160
	s_mov_b64 exec, vcc
	ds_write_b128 v236, v[194:197]
	ds_write_b128 v236, v[198:201] offset:64
	ds_write_b128 v236, v[202:205] offset:128
	ds_write_b128 v236, v[206:209] offset:192
	ds_write_b128 v236, v[210:213] offset:512
	ds_write_b128 v236, v[214:217] offset:576
	ds_write_b128 v236, v[218:221] offset:640
	ds_write_b128 v236, v[222:225] offset:704
	s_mov_b64 exec, -1
	s_waitcnt lgkmcnt(0)
	s_add_u32 s34, s34, s57
	s_addc_u32 s35, s35, 0
	s_lshl_b32 s57, s32, 13
	s_add_u32 s2, s2, s57
	s_addc_u32 s3, s3, 0
	s_cmp_eq_u32 s32, 0
	s_cselect_b32 s0, s0, s36
	s_cselect_b32 s1, s1, s37
	s_add_u32 s94, s94, 0x1c00000
	s_addc_u32 s95, s95, 0
	v_readfirstlane_b32 s32, v167
	s_barrier
	s_cmp_lt_u32 s32, 0x100
	s_cbranch_scc0 .Lgo_fz_w1
	v_lshlrev_b32_e32 v238, 2, v167
	v_add_u32_e32 v239, 0x20000, v238
	ds_read_b32 v240, v239
	ds_read_b32 v241, v239 offset:1024
	ds_read_b32 v242, v239 offset:2048
	ds_read_b32 v243, v239 offset:3072
	v_add_u32_e32 v244, s48, v238
	s_waitcnt lgkmcnt(0)
	v_add_f32_e32 v240, v240, v241
	v_add_f32_e32 v240, v240, v242
	v_add_f32_e32 v240, v240, v243
	global_store_dword v244, v240, s[94:95] sc0 sc1
	s_waitcnt vmcnt(0)

.Lgo_fz_no:
	s_lshl_b32 s32, s16, 3
	s_cmp_eq_u32 s32, s46
	s_cbranch_scc1 .Lgo_sk_dec
	s_cmpk_lt_i32 s44, 0x200
	s_cbranch_scc1 .Lgo_sk_dec
	s_sub_u32 s32, s44, 0x200
	s_lshr_b32 s94, s32, 5
	s_and_b32 s32, s32, 31
	s_add_u32 s2, s32, 0x200
	s_mov_b32 s95, 4
	s_cmp_eq_u32 s94, 0
	s_cselect_b32 s3, 1, 2
	s_lshl_b32 s94, s94, 10
